# scan loaders allow four chunks in flight instead of nine
# baseline (speedup 1.0000x reference)
; #define SP_BAR() asm volatile("s_waitcnt lgkmcnt(0)\n\ts_barrier" ::: "memory")
; #define SP_WAIT() asm volatile("s_waitcnt vmcnt(36)" ::: "memory")
; __device__ __forceinline__ void p3_rwkv_state(Frame& F, const Args& a) {
;     ...
;     if (loader) {
;         DmaPtrs P; rw_dma_init(a, P, head, ib, lw, lane);
;         for (int n = 0; n < SP_D; ++n) rw_dma_issue(P, lw, lane, lds0 + (unsigned)(n % SP_R) * SP_SLOT);
;         SP_WAIT();
;         SP_BAR();
.Lscan_ldbig_pro:
	s_add_i32 s16, s15, s14
	s_mov_b32 m0, s16
	s_add_i32 s15, s15, 0x2800
	global_load_lds_dwordx4 v[2:3], off
	global_load_lds_dwordx4 v[2:3], off offset:1024
	s_cmp_eq_u32 s15, 0x25800
	s_cselect_b32 s15, 0, s15
	v_lshl_add_u64 v[2:3], v[2:3], 0, s[6:7]
	s_add_i32 s18, s18, 1
	s_cmp_lt_u32 s18, 12
	s_cbranch_scc1 .Lscan_ldbig_pro
	s_waitcnt vmcnt(8)
	s_barrier
	s_mov_b32 s18, 0
	s_movk_i32 s17, 0x100

; #define SP_BAR() asm volatile("s_waitcnt lgkmcnt(0)\n\ts_barrier" ::: "memory")
; #define SP_WAIT() asm volatile("s_waitcnt vmcnt(36)" ::: "memory")
; __device__ __forceinline__ void p3_rwkv_state(Frame& F, const Args& a) {
;     ...
;         for (int n = 0; n < NC; n += 2) {
;             if (n + SP_D + 1 < NC) { rw_dma_issue(P, lw, lane, lds0 + (unsigned)((n + SP_D) % SP_R) * SP_SLOT); rw_dma_issue(P, lw, lane, lds0 + (unsigned)((n + SP_D + 1) % SP_R) * SP_SLOT); SP_WAIT(); }
;             else asm volatile("s_waitcnt vmcnt(0)" ::: "memory");
;             SP_BAR();
.Lscan_ldbig_go:
	s_add_i32 s16, s15, s14
	s_mov_b32 m0, s16
	s_add_i32 s15, s15, 0x2800
	global_load_lds_dwordx4 v[2:3], off
	global_load_lds_dwordx4 v[2:3], off offset:1024
	s_cmp_eq_u32 s15, 0x25800
	s_cselect_b32 s15, 0, s15
	v_lshl_add_u64 v[2:3], v[2:3], 0, s[6:7]
	s_add_i32 s16, s15, s14
	s_mov_b32 m0, s16
	s_add_i32 s15, s15, 0x2800
	global_load_lds_dwordx4 v[2:3], off
	global_load_lds_dwordx4 v[2:3], off offset:1024
	s_cmp_eq_u32 s15, 0x25800
	s_cselect_b32 s15, 0, s15
	v_lshl_add_u64 v[2:3], v[2:3], 0, s[6:7]
	s_waitcnt vmcnt(8)
	s_branch .Lscan_ldbig_bar

; #define SP_BAR() asm volatile("s_waitcnt lgkmcnt(0)\n\ts_barrier" ::: "memory")
; #define SP_WAIT() asm volatile("s_waitcnt vmcnt(36)" ::: "memory")
; __device__ __forceinline__ void p3_rwkv_state(Frame& F, const Args& a) {
;     ...
;     if (loader) {
;         DmaPtrs P; rw_dma_init(a, P, head, ib, lw, lane);
;         for (int n = 0; n < SP_D; ++n) rw_dma_issue(P, lw, lane, lds0 + (unsigned)(n % SP_R) * SP_SLOT);
;         SP_WAIT();
;         SP_BAR();
.Lscan_ldsmall_pro:
	s_add_i32 s16, s15, 0x2000
	s_mov_b32 m0, s16
	s_mov_b32 exec_hi, 0
	s_add_i32 s15, s15, 0x2800
	global_load_lds_dwordx4 v[2:3], off
	global_load_lds_dwordx4 v[4:5], off offset:512
	global_load_lds_dwordx4 v[6:7], off offset:1024
	s_mov_b32 exec_lo, 0xffff
	s_cmp_eq_u32 s15, 0x25800
	global_load_lds_dwordx4 v[8:9], off offset:1536
	s_mov_b64 exec, -1
	s_cselect_b32 s15, 0, s15
	v_lshl_add_u64 v[2:3], v[2:3], 0, s[6:7]
	v_lshl_add_u64 v[4:5], v[4:5], 0, s[6:7]
	v_lshl_add_u64 v[6:7], v[6:7], 0, s[6:7]
	v_lshl_add_u64 v[8:9], v[8:9], 0, s[10:11]
	s_add_i32 s18, s18, 1
	s_cmp_lt_u32 s18, 12
	s_cbranch_scc1 .Lscan_ldsmall_pro
	s_waitcnt vmcnt(16)
	s_barrier
	s_mov_b32 s18, 0
	s_movk_i32 s17, 0x100

; #define SP_BAR() asm volatile("s_waitcnt lgkmcnt(0)\n\ts_barrier" ::: "memory")
; #define SP_WAIT() asm volatile("s_waitcnt vmcnt(36)" ::: "memory")
; __device__ __forceinline__ void p3_rwkv_state(Frame& F, const Args& a) {
;     ...
;         for (int n = 0; n < NC; n += 2) {
;             if (n + SP_D + 1 < NC) { rw_dma_issue(P, lw, lane, lds0 + (unsigned)((n + SP_D) % SP_R) * SP_SLOT); rw_dma_issue(P, lw, lane, lds0 + (unsigned)((n + SP_D + 1) % SP_R) * SP_SLOT); SP_WAIT(); }
;             else asm volatile("s_waitcnt vmcnt(0)" ::: "memory");
;             SP_BAR();
.Lscan_ldsmall_go:
	s_add_i32 s16, s15, 0x2000
	s_mov_b32 m0, s16
	s_mov_b32 exec_hi, 0
	s_add_i32 s15, s15, 0x2800
	global_load_lds_dwordx4 v[2:3], off
	global_load_lds_dwordx4 v[4:5], off offset:512
	global_load_lds_dwordx4 v[6:7], off offset:1024
	s_mov_b32 exec_lo, 0xffff
	s_cmp_eq_u32 s15, 0x25800
	global_load_lds_dwordx4 v[8:9], off offset:1536
	s_mov_b64 exec, -1
	s_cselect_b32 s15, 0, s15
	v_lshl_add_u64 v[2:3], v[2:3], 0, s[6:7]
	v_lshl_add_u64 v[4:5], v[4:5], 0, s[6:7]
	v_lshl_add_u64 v[6:7], v[6:7], 0, s[6:7]
	v_lshl_add_u64 v[8:9], v[8:9], 0, s[10:11]
	s_add_i32 s16, s15, 0x2000
	s_mov_b32 m0, s16
	s_mov_b32 exec_hi, 0
	s_add_i32 s15, s15, 0x2800
	global_load_lds_dwordx4 v[2:3], off
	global_load_lds_dwordx4 v[4:5], off offset:512
	global_load_lds_dwordx4 v[6:7], off offset:1024
	s_mov_b32 exec_lo, 0xffff
	s_cmp_eq_u32 s15, 0x25800
	global_load_lds_dwordx4 v[8:9], off offset:1536
	s_mov_b64 exec, -1
	s_cselect_b32 s15, 0, s15
	v_lshl_add_u64 v[2:3], v[2:3], 0, s[6:7]
	v_lshl_add_u64 v[4:5], v[4:5], 0, s[6:7]
	v_lshl_add_u64 v[6:7], v[6:7], 0, s[6:7]
	v_lshl_add_u64 v[8:9], v[8:9], 0, s[10:11]
	s_waitcnt vmcnt(16)
	s_branch .Lscan_ldsmall_bar
